# v22_topgen
# speedup vs baseline: 1.0096x; 1.0007x over previous
; __device__ __forceinline__ unsigned xb_ld(unsigned* p)              { return __hip_atomic_load(p, __ATOMIC_RELAXED, __HIP_MEMORY_SCOPE_AGENT); }
; __device__ __forceinline__ unsigned xb_add(unsigned* p, unsigned v) { return __hip_atomic_fetch_add(p, v, __ATOMIC_RELAXED, __HIP_MEMORY_SCOPE_AGENT); }
; #define XB_SPIN(cond, bar) do { unsigned _sp = 0; while (cond) { __builtin_amdgcn_s_sleep(1); \
;     if ((++_sp & 255u) == 0u) { if (xb_ld(&(bar)[XB_TMO])) break; if (_sp > XB_SPIN_CAP) { atomicAdd(&(bar)[XB_TMO], 1u); break; } } } } while (0)
; __device__ __forceinline__ void xcd_barrier(const XcdBarrier& b) {
;     ...
;         const unsigned old = xb_add(&bar[XB_XSUB(b.x)], 1u);
;         const unsigned gen = old / nloc;
;         if (old + 1u == (gen + 1u) * nloc) {
;             __builtin_amdgcn_fence(__ATOMIC_RELEASE, "agent");
;             asm volatile("s_waitcnt vmcnt(0)" ::: "memory");
;             const unsigned og = xb_add(&bar[XB_TOP], 1u);
;             const unsigned tg = og / nx;
;             if (og + 1u == (tg + 1u) * nx) xb_add(&bar[XB_TOPGEN], 1u);
;             else XB_SPIN(xb_ld(&bar[XB_TOPGEN]) == tg, bar);
;             __builtin_amdgcn_fence(__ATOMIC_ACQUIRE, "agent");
;             xb_add(&bar[XB_XGEN(b.x)], 1u);
;             asm volatile("s_waitcnt vmcnt(0)" ::: "memory");
;         } else {
;             XB_SPIN(xb_ld(&bar[XB_XGEN(b.x)]) == gen, bar);
.LBB0_74:
	s_or_b64 exec, exec, s[14:15]
	v_cvt_f32_u32_e32 v5, v2
	s_waitcnt vmcnt(0)
	v_readfirstlane_b32 s3, v3
	v_sub_u32_e32 v3, 0, v2
	v_rcp_iflag_f32_e32 v5, v5
	v_add_u32_e32 v6, s3, v1
	v_mul_f32_e32 v5, 0x4f7ffffe, v5
	v_cvt_u32_f32_e32 v5, v5
	v_mul_lo_u32 v1, v3, v5
	v_mul_hi_u32 v1, v5, v1
	v_add_u32_e32 v1, v5, v1
	v_mul_hi_u32 v1, v6, v1
	v_mul_lo_u32 v3, v1, v2
	v_sub_u32_e32 v3, v6, v3
	v_add_u32_e32 v5, 1, v1
	v_cmp_ge_u32_e32 vcc, v3, v2
	s_nop 1
	v_cndmask_b32_e32 v1, v1, v5, vcc
	v_sub_u32_e32 v5, v3, v2
	v_cndmask_b32_e32 v3, v3, v5, vcc
	v_add_u32_e32 v5, 1, v1
	v_cmp_ge_u32_e32 vcc, v3, v2
	v_add_u32_e32 v3, 1, v6
	s_nop 0
	v_cndmask_b32_e32 v1, v1, v5, vcc
	v_mul_lo_u32 v5, v2, v1
	v_add_u32_e32 v2, v5, v2
	v_cmp_ne_u32_e32 vcc, v3, v2
	s_and_saveexec_b64 s[6:7], vcc
	s_xor_b64 s[12:13], exec, s[6:7]
	s_cbranch_execz .LBB0_88
	s_waitcnt lgkmcnt(0)
	buffer_inv sc1
	v_mov_b32_e32 v0, 0x33500
	global_load_dword v0, v0, s[18:19] sc1
	s_add_u32 s26, s18, 0x33500
	s_addc_u32 s27, s19, 0
	s_waitcnt vmcnt(0)
	v_cmp_eq_u32_e32 vcc, v0, v1
	s_and_saveexec_b64 s[14:15], vcc
	s_cbranch_execz .LBB0_87
	s_add_u32 s22, s18, 0x30200
	s_addc_u32 s23, s19, 0
	s_mov_b32 s3, 1
	s_mov_b64 s[28:29], 0
	v_mov_b32_e32 v0, 0
	s_branch .LBB0_78

; __device__ __forceinline__ unsigned xb_ld(unsigned* p)              { return __hip_atomic_load(p, __ATOMIC_RELAXED, __HIP_MEMORY_SCOPE_AGENT); }
; __device__ __forceinline__ unsigned xb_add(unsigned* p, unsigned v) { return __hip_atomic_fetch_add(p, v, __ATOMIC_RELAXED, __HIP_MEMORY_SCOPE_AGENT); }
; #define XB_SPIN(cond, bar) do { unsigned _sp = 0; while (cond) { __builtin_amdgcn_s_sleep(1); \
;     if ((++_sp & 255u) == 0u) { if (xb_ld(&(bar)[XB_TMO])) break; if (_sp > XB_SPIN_CAP) { atomicAdd(&(bar)[XB_TMO], 1u); break; } } } } while (0)
; __device__ __forceinline__ void xcd_barrier(const XcdBarrier& b) {
;     ...
;             const unsigned og = xb_add(&bar[XB_TOP], 1u);
;             const unsigned tg = og / nx;
;             if (og + 1u == (tg + 1u) * nx) xb_add(&bar[XB_TOPGEN], 1u);
;             else XB_SPIN(xb_ld(&bar[XB_TOPGEN]) == tg, bar);
;             __builtin_amdgcn_fence(__ATOMIC_ACQUIRE, "agent");
;             xb_add(&bar[XB_XGEN(b.x)], 1u);
;             asm volatile("s_waitcnt vmcnt(0)" ::: "memory");
.LBB0_105:
	s_or_b64 exec, exec, s[12:13]
	s_mov_b64 s[12:13], exec
	v_mbcnt_lo_u32_b32 v0, s12, 0
	v_mbcnt_hi_u32_b32 v0, s13, v0
	v_cmp_eq_u32_e32 vcc, 0, v0
	s_waitcnt vmcnt(0)
	s_and_saveexec_b64 s[14:15], vcc
	s_cbranch_execz .LBB0_107
	s_bcnt1_i32_b64 s3, s[12:13]
.LBB0_107:
	s_or_b64 exec, exec, s[14:15]
	s_waitcnt vmcnt(0)

; __device__ __forceinline__ unsigned xb_ld(unsigned* p)              { return __hip_atomic_load(p, __ATOMIC_RELAXED, __HIP_MEMORY_SCOPE_AGENT); }
; __device__ __forceinline__ unsigned xb_add(unsigned* p, unsigned v) { return __hip_atomic_fetch_add(p, v, __ATOMIC_RELAXED, __HIP_MEMORY_SCOPE_AGENT); }
; #define XB_SPIN(cond, bar) do { unsigned _sp = 0; while (cond) { __builtin_amdgcn_s_sleep(1); \
;     if ((++_sp & 255u) == 0u) { if (xb_ld(&(bar)[XB_TMO])) break; if (_sp > XB_SPIN_CAP) { atomicAdd(&(bar)[XB_TMO], 1u); break; } } } } while (0)
; __device__ __forceinline__ void xcd_barrier(const XcdBarrier& b) {
;     ...
;         const unsigned old = xb_add(&bar[XB_XSUB(b.x)], 1u);
;         const unsigned gen = old / nloc;
;         if (old + 1u == (gen + 1u) * nloc) {
;             __builtin_amdgcn_fence(__ATOMIC_RELEASE, "agent");
;             asm volatile("s_waitcnt vmcnt(0)" ::: "memory");
;             const unsigned og = xb_add(&bar[XB_TOP], 1u);
;             const unsigned tg = og / nx;
;             if (og + 1u == (tg + 1u) * nx) xb_add(&bar[XB_TOPGEN], 1u);
;             else XB_SPIN(xb_ld(&bar[XB_TOPGEN]) == tg, bar);
;             __builtin_amdgcn_fence(__ATOMIC_ACQUIRE, "agent");
;             xb_add(&bar[XB_XGEN(b.x)], 1u);
;             asm volatile("s_waitcnt vmcnt(0)" ::: "memory");
;         } else {
;             XB_SPIN(xb_ld(&bar[XB_XGEN(b.x)]) == gen, bar);
.Lxs_nofirst_0:
	v_mov_b32_e32 v0, 0x33500
	global_load_dword v0, v0, s[18:19] sc1
	s_add_u32 s28, s18, 0x33500
	s_addc_u32 s29, s19, 0
	s_waitcnt vmcnt(0)
	v_cmp_eq_u32_e32 vcc, v0, v1
	s_and_saveexec_b64 s[14:15], vcc
	s_cbranch_execz .LBB0_141
	s_add_u32 s26, s18, 0x30200
	s_addc_u32 s27, s19, 0
	s_mov_b32 s3, 1
	s_mov_b64 s[30:31], 0
	v_mov_b32_e32 v0, 0
	s_branch .LBB0_132

; __device__ __forceinline__ unsigned xb_ld(unsigned* p)              { return __hip_atomic_load(p, __ATOMIC_RELAXED, __HIP_MEMORY_SCOPE_AGENT); }
; __device__ __forceinline__ unsigned xb_add(unsigned* p, unsigned v) { return __hip_atomic_fetch_add(p, v, __ATOMIC_RELAXED, __HIP_MEMORY_SCOPE_AGENT); }
; #define XB_SPIN(cond, bar) do { unsigned _sp = 0; while (cond) { __builtin_amdgcn_s_sleep(1); \
;     if ((++_sp & 255u) == 0u) { if (xb_ld(&(bar)[XB_TMO])) break; if (_sp > XB_SPIN_CAP) { atomicAdd(&(bar)[XB_TMO], 1u); break; } } } } while (0)
; __device__ __forceinline__ void xcd_barrier(const XcdBarrier& b) {
;     ...
;             const unsigned og = xb_add(&bar[XB_TOP], 1u);
;             const unsigned tg = og / nx;
;             if (og + 1u == (tg + 1u) * nx) xb_add(&bar[XB_TOPGEN], 1u);
;             else XB_SPIN(xb_ld(&bar[XB_TOPGEN]) == tg, bar);
;             __builtin_amdgcn_fence(__ATOMIC_ACQUIRE, "agent");
;             xb_add(&bar[XB_XGEN(b.x)], 1u);
;             asm volatile("s_waitcnt vmcnt(0)" ::: "memory");
.LBB0_159:
	s_or_b64 exec, exec, s[12:13]
	s_mov_b64 s[12:13], exec
	v_mbcnt_lo_u32_b32 v0, s12, 0
	v_mbcnt_hi_u32_b32 v0, s13, v0
	v_cmp_eq_u32_e32 vcc, 0, v0
	s_waitcnt vmcnt(0)
	s_and_saveexec_b64 s[14:15], vcc
	s_cbranch_execz .LBB0_161
	s_bcnt1_i32_b64 s3, s[12:13]
.LBB0_161:
	s_or_b64 exec, exec, s[14:15]
	s_waitcnt vmcnt(0)

; __device__ __forceinline__ unsigned xb_ld(unsigned* p)              { return __hip_atomic_load(p, __ATOMIC_RELAXED, __HIP_MEMORY_SCOPE_AGENT); }
; __device__ __forceinline__ unsigned xb_add(unsigned* p, unsigned v) { return __hip_atomic_fetch_add(p, v, __ATOMIC_RELAXED, __HIP_MEMORY_SCOPE_AGENT); }
; #define XB_SPIN(cond, bar) do { unsigned _sp = 0; while (cond) { __builtin_amdgcn_s_sleep(1); \
;     if ((++_sp & 255u) == 0u) { if (xb_ld(&(bar)[XB_TMO])) break; if (_sp > XB_SPIN_CAP) { atomicAdd(&(bar)[XB_TMO], 1u); break; } } } } while (0)
; __device__ __forceinline__ void xcd_barrier(const XcdBarrier& b) {
;     ...
;         const unsigned old = xb_add(&bar[XB_XSUB(b.x)], 1u);
;         const unsigned gen = old / nloc;
;         if (old + 1u == (gen + 1u) * nloc) {
;             __builtin_amdgcn_fence(__ATOMIC_RELEASE, "agent");
;             asm volatile("s_waitcnt vmcnt(0)" ::: "memory");
;             const unsigned og = xb_add(&bar[XB_TOP], 1u);
;             const unsigned tg = og / nx;
;             if (og + 1u == (tg + 1u) * nx) xb_add(&bar[XB_TOPGEN], 1u);
;             else XB_SPIN(xb_ld(&bar[XB_TOPGEN]) == tg, bar);
;             __builtin_amdgcn_fence(__ATOMIC_ACQUIRE, "agent");
;             xb_add(&bar[XB_XGEN(b.x)], 1u);
;             asm volatile("s_waitcnt vmcnt(0)" ::: "memory");
;         } else {
;             XB_SPIN(xb_ld(&bar[XB_XGEN(b.x)]) == gen, bar);
.Lxs_nofirst_1:
	v_mov_b32_e32 v0, 0x33500
	global_load_dword v0, v0, s[18:19] sc1
	s_add_u32 s30, s18, 0x33500
	s_addc_u32 s31, s19, 0
	s_waitcnt vmcnt(0)
	v_cmp_eq_u32_e32 vcc, v0, v1
	s_and_saveexec_b64 s[26:27], vcc
	s_cbranch_execz .LBB0_205
	s_add_u32 s28, s18, 0x30200
	s_addc_u32 s29, s19, 0
	s_mov_b32 s3, 1
	s_mov_b64 s[34:35], 0
	v_mov_b32_e32 v0, 0
	s_branch .LBB0_196

; __device__ __forceinline__ unsigned xb_ld(unsigned* p)              { return __hip_atomic_load(p, __ATOMIC_RELAXED, __HIP_MEMORY_SCOPE_AGENT); }
; __device__ __forceinline__ unsigned xb_add(unsigned* p, unsigned v) { return __hip_atomic_fetch_add(p, v, __ATOMIC_RELAXED, __HIP_MEMORY_SCOPE_AGENT); }
; #define XB_SPIN(cond, bar) do { unsigned _sp = 0; while (cond) { __builtin_amdgcn_s_sleep(1); \
;     if ((++_sp & 255u) == 0u) { if (xb_ld(&(bar)[XB_TMO])) break; if (_sp > XB_SPIN_CAP) { atomicAdd(&(bar)[XB_TMO], 1u); break; } } } } while (0)
; __device__ __forceinline__ void xcd_barrier(const XcdBarrier& b) {
;     ...
;             const unsigned og = xb_add(&bar[XB_TOP], 1u);
;             const unsigned tg = og / nx;
;             if (og + 1u == (tg + 1u) * nx) xb_add(&bar[XB_TOPGEN], 1u);
;             else XB_SPIN(xb_ld(&bar[XB_TOPGEN]) == tg, bar);
;             __builtin_amdgcn_fence(__ATOMIC_ACQUIRE, "agent");
;             xb_add(&bar[XB_XGEN(b.x)], 1u);
;             asm volatile("s_waitcnt vmcnt(0)" ::: "memory");
.LBB0_223:
	s_or_b64 exec, exec, s[12:13]
	s_mov_b64 s[12:13], exec
	v_mbcnt_lo_u32_b32 v0, s12, 0
	v_mbcnt_hi_u32_b32 v0, s13, v0
	v_cmp_eq_u32_e32 vcc, 0, v0
	s_waitcnt vmcnt(0)
	s_and_saveexec_b64 s[26:27], vcc
	s_cbranch_execz .LBB0_225
	s_bcnt1_i32_b64 s3, s[12:13]
.LBB0_225:
	s_or_b64 exec, exec, s[26:27]
	s_waitcnt vmcnt(0)

; __device__ __forceinline__ unsigned xb_ld(unsigned* p)              { return __hip_atomic_load(p, __ATOMIC_RELAXED, __HIP_MEMORY_SCOPE_AGENT); }
; __device__ __forceinline__ unsigned xb_add(unsigned* p, unsigned v) { return __hip_atomic_fetch_add(p, v, __ATOMIC_RELAXED, __HIP_MEMORY_SCOPE_AGENT); }
; #define XB_SPIN(cond, bar) do { unsigned _sp = 0; while (cond) { __builtin_amdgcn_s_sleep(1); \
;     if ((++_sp & 255u) == 0u) { if (xb_ld(&(bar)[XB_TMO])) break; if (_sp > XB_SPIN_CAP) { atomicAdd(&(bar)[XB_TMO], 1u); break; } } } } while (0)
; __device__ __forceinline__ void xcd_barrier(const XcdBarrier& b) {
;     ...
;         const unsigned old = xb_add(&bar[XB_XSUB(b.x)], 1u);
;         const unsigned gen = old / nloc;
;         if (old + 1u == (gen + 1u) * nloc) {
;             __builtin_amdgcn_fence(__ATOMIC_RELEASE, "agent");
;             asm volatile("s_waitcnt vmcnt(0)" ::: "memory");
;             const unsigned og = xb_add(&bar[XB_TOP], 1u);
;             const unsigned tg = og / nx;
;             if (og + 1u == (tg + 1u) * nx) xb_add(&bar[XB_TOPGEN], 1u);
;             else XB_SPIN(xb_ld(&bar[XB_TOPGEN]) == tg, bar);
;             __builtin_amdgcn_fence(__ATOMIC_ACQUIRE, "agent");
;             xb_add(&bar[XB_XGEN(b.x)], 1u);
;             asm volatile("s_waitcnt vmcnt(0)" ::: "memory");
;         } else {
;             XB_SPIN(xb_ld(&bar[XB_XGEN(b.x)]) == gen, bar);
.Lxs_nofirst_2:
	v_mov_b32_e32 v0, 0x33500
	global_load_dword v0, v0, s[18:19] sc1
	s_add_u32 s34, s18, 0x33500
	s_addc_u32 s35, s19, 0
	s_waitcnt vmcnt(0)
	v_cmp_eq_u32_e32 vcc, v0, v1
	s_and_saveexec_b64 s[28:29], vcc
	s_cbranch_execz .LBB0_281
	s_add_u32 s30, s18, 0x30200
	s_addc_u32 s31, s19, 0
	s_mov_b32 s3, 1
	s_mov_b64 s[36:37], 0
	v_mov_b32_e32 v0, 0
	s_branch .LBB0_272

; __device__ __forceinline__ unsigned xb_ld(unsigned* p)              { return __hip_atomic_load(p, __ATOMIC_RELAXED, __HIP_MEMORY_SCOPE_AGENT); }
; __device__ __forceinline__ unsigned xb_add(unsigned* p, unsigned v) { return __hip_atomic_fetch_add(p, v, __ATOMIC_RELAXED, __HIP_MEMORY_SCOPE_AGENT); }
; #define XB_SPIN(cond, bar) do { unsigned _sp = 0; while (cond) { __builtin_amdgcn_s_sleep(1); \
;     if ((++_sp & 255u) == 0u) { if (xb_ld(&(bar)[XB_TMO])) break; if (_sp > XB_SPIN_CAP) { atomicAdd(&(bar)[XB_TMO], 1u); break; } } } } while (0)
; __device__ __forceinline__ void xcd_barrier(const XcdBarrier& b) {
;     ...
;             const unsigned og = xb_add(&bar[XB_TOP], 1u);
;             const unsigned tg = og / nx;
;             if (og + 1u == (tg + 1u) * nx) xb_add(&bar[XB_TOPGEN], 1u);
;             else XB_SPIN(xb_ld(&bar[XB_TOPGEN]) == tg, bar);
;             __builtin_amdgcn_fence(__ATOMIC_ACQUIRE, "agent");
;             xb_add(&bar[XB_XGEN(b.x)], 1u);
;             asm volatile("s_waitcnt vmcnt(0)" ::: "memory");
.LBB0_299:
	s_or_b64 exec, exec, s[12:13]
	s_mov_b64 s[12:13], exec
	v_mbcnt_lo_u32_b32 v0, s12, 0
	v_mbcnt_hi_u32_b32 v0, s13, v0
	v_cmp_eq_u32_e32 vcc, 0, v0
	s_waitcnt vmcnt(0)
	s_and_saveexec_b64 s[28:29], vcc
	s_cbranch_execz .LBB0_301
	s_bcnt1_i32_b64 s3, s[12:13]
.LBB0_301:
	s_or_b64 exec, exec, s[28:29]
	s_waitcnt vmcnt(0)

; __device__ __forceinline__ unsigned xb_ld(unsigned* p)              { return __hip_atomic_load(p, __ATOMIC_RELAXED, __HIP_MEMORY_SCOPE_AGENT); }
; __device__ __forceinline__ unsigned xb_add(unsigned* p, unsigned v) { return __hip_atomic_fetch_add(p, v, __ATOMIC_RELAXED, __HIP_MEMORY_SCOPE_AGENT); }
; #define XB_SPIN(cond, bar) do { unsigned _sp = 0; while (cond) { __builtin_amdgcn_s_sleep(1); \
;     if ((++_sp & 255u) == 0u) { if (xb_ld(&(bar)[XB_TMO])) break; if (_sp > XB_SPIN_CAP) { atomicAdd(&(bar)[XB_TMO], 1u); break; } } } } while (0)
; __device__ __forceinline__ void xcd_barrier(const XcdBarrier& b) {
;     ...
;             const unsigned og = xb_add(&bar[XB_TOP], 1u);
;             const unsigned tg = og / nx;
;             if (og + 1u == (tg + 1u) * nx) xb_add(&bar[XB_TOPGEN], 1u);
;             else XB_SPIN(xb_ld(&bar[XB_TOPGEN]) == tg, bar);
;             __builtin_amdgcn_fence(__ATOMIC_ACQUIRE, "agent");
;             xb_add(&bar[XB_XGEN(b.x)], 1u);
;             asm volatile("s_waitcnt vmcnt(0)" ::: "memory");
.LBB0_353:
	s_or_b64 exec, exec, s[12:13]
	s_mov_b64 s[12:13], exec
	v_mbcnt_lo_u32_b32 v0, s12, 0
	v_mbcnt_hi_u32_b32 v0, s13, v0
	v_cmp_eq_u32_e32 vcc, 0, v0
	s_waitcnt vmcnt(0)
	s_and_saveexec_b64 s[28:29], vcc
	s_cbranch_execz .LBB0_355
	s_bcnt1_i32_b64 s3, s[12:13]
.LBB0_355:
	s_or_b64 exec, exec, s[28:29]
	s_waitcnt vmcnt(0)

; __device__ __forceinline__ unsigned xb_ld(unsigned* p)              { return __hip_atomic_load(p, __ATOMIC_RELAXED, __HIP_MEMORY_SCOPE_AGENT); }
; __device__ __forceinline__ unsigned xb_add(unsigned* p, unsigned v) { return __hip_atomic_fetch_add(p, v, __ATOMIC_RELAXED, __HIP_MEMORY_SCOPE_AGENT); }
; #define XB_SPIN(cond, bar) do { unsigned _sp = 0; while (cond) { __builtin_amdgcn_s_sleep(1); \
;     if ((++_sp & 255u) == 0u) { if (xb_ld(&(bar)[XB_TMO])) break; if (_sp > XB_SPIN_CAP) { atomicAdd(&(bar)[XB_TMO], 1u); break; } } } } while (0)
; __device__ __forceinline__ void xcd_barrier(const XcdBarrier& b) {
;     ...
;             const unsigned og = xb_add(&bar[XB_TOP], 1u);
;             const unsigned tg = og / nx;
;             if (og + 1u == (tg + 1u) * nx) xb_add(&bar[XB_TOPGEN], 1u);
;             else XB_SPIN(xb_ld(&bar[XB_TOPGEN]) == tg, bar);
;             __builtin_amdgcn_fence(__ATOMIC_ACQUIRE, "agent");
;             xb_add(&bar[XB_XGEN(b.x)], 1u);
;             asm volatile("s_waitcnt vmcnt(0)" ::: "memory");
.LBB0_445:
	s_or_b64 exec, exec, s[14:15]
	s_mov_b64 s[14:15], exec
	v_mbcnt_lo_u32_b32 v0, s14, 0
	v_mbcnt_hi_u32_b32 v0, s15, v0
	v_cmp_eq_u32_e32 vcc, 0, v0
	s_waitcnt vmcnt(0)
	s_and_saveexec_b64 s[28:29], vcc
	s_cbranch_execz .LBB0_447
	s_bcnt1_i32_b64 s3, s[14:15]
.LBB0_447:
	s_or_b64 exec, exec, s[28:29]
	s_waitcnt vmcnt(0)

; __device__ __forceinline__ unsigned xb_ld(unsigned* p)              { return __hip_atomic_load(p, __ATOMIC_RELAXED, __HIP_MEMORY_SCOPE_AGENT); }
; __device__ __forceinline__ unsigned xb_add(unsigned* p, unsigned v) { return __hip_atomic_fetch_add(p, v, __ATOMIC_RELAXED, __HIP_MEMORY_SCOPE_AGENT); }
; #define XB_SPIN(cond, bar) do { unsigned _sp = 0; while (cond) { __builtin_amdgcn_s_sleep(1); \
;     if ((++_sp & 255u) == 0u) { if (xb_ld(&(bar)[XB_TMO])) break; if (_sp > XB_SPIN_CAP) { atomicAdd(&(bar)[XB_TMO], 1u); break; } } } } while (0)
; __device__ __forceinline__ void xcd_barrier(const XcdBarrier& b) {
;     ...
;         const unsigned old = xb_add(&bar[XB_XSUB(b.x)], 1u);
;         const unsigned gen = old / nloc;
;         if (old + 1u == (gen + 1u) * nloc) {
;             __builtin_amdgcn_fence(__ATOMIC_RELEASE, "agent");
;             asm volatile("s_waitcnt vmcnt(0)" ::: "memory");
;             const unsigned og = xb_add(&bar[XB_TOP], 1u);
;             const unsigned tg = og / nx;
;             if (og + 1u == (tg + 1u) * nx) xb_add(&bar[XB_TOPGEN], 1u);
;             else XB_SPIN(xb_ld(&bar[XB_TOPGEN]) == tg, bar);
;             __builtin_amdgcn_fence(__ATOMIC_ACQUIRE, "agent");
;             xb_add(&bar[XB_XGEN(b.x)], 1u);
;             asm volatile("s_waitcnt vmcnt(0)" ::: "memory");
;         } else {
;             XB_SPIN(xb_ld(&bar[XB_XGEN(b.x)]) == gen, bar);
.Lxs_nofirst_5:
	v_mov_b32_e32 v0, 0x33500
	global_load_dword v0, v0, s[18:19] sc1
	s_add_u32 s36, s18, 0x33500
	s_addc_u32 s37, s19, 0
	s_waitcnt vmcnt(0)
	v_cmp_eq_u32_e32 vcc, v0, v1
	s_and_saveexec_b64 s[30:31], vcc
	s_cbranch_execz .LBB0_484
	s_add_u32 s34, s18, 0x30200
	s_addc_u32 s35, s19, 0
	s_mov_b32 s3, 1
	s_mov_b64 s[38:39], 0
	v_mov_b32_e32 v0, 0
	s_branch .LBB0_475

; __device__ __forceinline__ unsigned xb_ld(unsigned* p)              { return __hip_atomic_load(p, __ATOMIC_RELAXED, __HIP_MEMORY_SCOPE_AGENT); }
; __device__ __forceinline__ unsigned xb_add(unsigned* p, unsigned v) { return __hip_atomic_fetch_add(p, v, __ATOMIC_RELAXED, __HIP_MEMORY_SCOPE_AGENT); }
; #define XB_SPIN(cond, bar) do { unsigned _sp = 0; while (cond) { __builtin_amdgcn_s_sleep(1); \
;     if ((++_sp & 255u) == 0u) { if (xb_ld(&(bar)[XB_TMO])) break; if (_sp > XB_SPIN_CAP) { atomicAdd(&(bar)[XB_TMO], 1u); break; } } } } while (0)
; __device__ __forceinline__ void xcd_barrier(const XcdBarrier& b) {
;     ...
;             const unsigned og = xb_add(&bar[XB_TOP], 1u);
;             const unsigned tg = og / nx;
;             if (og + 1u == (tg + 1u) * nx) xb_add(&bar[XB_TOPGEN], 1u);
;             else XB_SPIN(xb_ld(&bar[XB_TOPGEN]) == tg, bar);
;             __builtin_amdgcn_fence(__ATOMIC_ACQUIRE, "agent");
;             xb_add(&bar[XB_XGEN(b.x)], 1u);
;             asm volatile("s_waitcnt vmcnt(0)" ::: "memory");
.LBB0_502:
	s_or_b64 exec, exec, s[28:29]
	s_mov_b64 s[28:29], exec
	v_mbcnt_lo_u32_b32 v0, s28, 0
	v_mbcnt_hi_u32_b32 v0, s29, v0
	v_cmp_eq_u32_e32 vcc, 0, v0
	s_waitcnt vmcnt(0)
	s_and_saveexec_b64 s[30:31], vcc
	s_cbranch_execz .LBB0_504
	s_bcnt1_i32_b64 s3, s[28:29]
.LBB0_504:
	s_or_b64 exec, exec, s[30:31]
	s_waitcnt vmcnt(0)

; __device__ __forceinline__ unsigned xb_ld(unsigned* p)              { return __hip_atomic_load(p, __ATOMIC_RELAXED, __HIP_MEMORY_SCOPE_AGENT); }
; __device__ __forceinline__ unsigned xb_add(unsigned* p, unsigned v) { return __hip_atomic_fetch_add(p, v, __ATOMIC_RELAXED, __HIP_MEMORY_SCOPE_AGENT); }
; #define XB_SPIN(cond, bar) do { unsigned _sp = 0; while (cond) { __builtin_amdgcn_s_sleep(1); \
;     if ((++_sp & 255u) == 0u) { if (xb_ld(&(bar)[XB_TMO])) break; if (_sp > XB_SPIN_CAP) { atomicAdd(&(bar)[XB_TMO], 1u); break; } } } } while (0)
; __device__ __forceinline__ void xcd_barrier(const XcdBarrier& b) {
;     ...
;             const unsigned og = xb_add(&bar[XB_TOP], 1u);
;             const unsigned tg = og / nx;
;             if (og + 1u == (tg + 1u) * nx) xb_add(&bar[XB_TOPGEN], 1u);
;             else XB_SPIN(xb_ld(&bar[XB_TOPGEN]) == tg, bar);
;             __builtin_amdgcn_fence(__ATOMIC_ACQUIRE, "agent");
;             xb_add(&bar[XB_XGEN(b.x)], 1u);
;             asm volatile("s_waitcnt vmcnt(0)" ::: "memory");
.LBB0_559:
	s_or_b64 exec, exec, s[28:29]
	s_mov_b64 s[28:29], exec
	v_mbcnt_lo_u32_b32 v0, s28, 0
	v_mbcnt_hi_u32_b32 v0, s29, v0
	v_cmp_eq_u32_e32 vcc, 0, v0
	s_waitcnt vmcnt(0)
	s_and_saveexec_b64 s[30:31], vcc
	s_cbranch_execz .LBB0_561
	s_bcnt1_i32_b64 s3, s[28:29]
.LBB0_561:
	s_or_b64 exec, exec, s[30:31]
	s_waitcnt vmcnt(0)

; __device__ __forceinline__ unsigned xb_ld(unsigned* p)              { return __hip_atomic_load(p, __ATOMIC_RELAXED, __HIP_MEMORY_SCOPE_AGENT); }
; __device__ __forceinline__ unsigned xb_add(unsigned* p, unsigned v) { return __hip_atomic_fetch_add(p, v, __ATOMIC_RELAXED, __HIP_MEMORY_SCOPE_AGENT); }
; #define XB_SPIN(cond, bar) do { unsigned _sp = 0; while (cond) { __builtin_amdgcn_s_sleep(1); \
;     if ((++_sp & 255u) == 0u) { if (xb_ld(&(bar)[XB_TMO])) break; if (_sp > XB_SPIN_CAP) { atomicAdd(&(bar)[XB_TMO], 1u); break; } } } } while (0)
; __device__ __forceinline__ void xcd_barrier(const XcdBarrier& b) {
;     ...
;             const unsigned og = xb_add(&bar[XB_TOP], 1u);
;             const unsigned tg = og / nx;
;             if (og + 1u == (tg + 1u) * nx) xb_add(&bar[XB_TOPGEN], 1u);
;             else XB_SPIN(xb_ld(&bar[XB_TOPGEN]) == tg, bar);
;             __builtin_amdgcn_fence(__ATOMIC_ACQUIRE, "agent");
;             xb_add(&bar[XB_XGEN(b.x)], 1u);
;             asm volatile("s_waitcnt vmcnt(0)" ::: "memory");
.LBB0_707:
	s_or_b64 exec, exec, s[14:15]
	s_mov_b64 s[14:15], exec
	v_mbcnt_lo_u32_b32 v0, s14, 0
	v_mbcnt_hi_u32_b32 v0, s15, v0
	v_cmp_eq_u32_e32 vcc, 0, v0
	s_waitcnt vmcnt(0)
	s_and_saveexec_b64 s[28:29], vcc
	s_cbranch_execz .LBB0_709
	s_bcnt1_i32_b64 s3, s[14:15]
.LBB0_709:
	s_or_b64 exec, exec, s[28:29]
	s_waitcnt vmcnt(0)

; __device__ __forceinline__ unsigned xb_ld(unsigned* p)              { return __hip_atomic_load(p, __ATOMIC_RELAXED, __HIP_MEMORY_SCOPE_AGENT); }
; __device__ __forceinline__ unsigned xb_add(unsigned* p, unsigned v) { return __hip_atomic_fetch_add(p, v, __ATOMIC_RELAXED, __HIP_MEMORY_SCOPE_AGENT); }
; #define XB_SPIN(cond, bar) do { unsigned _sp = 0; while (cond) { __builtin_amdgcn_s_sleep(1); \
;     if ((++_sp & 255u) == 0u) { if (xb_ld(&(bar)[XB_TMO])) break; if (_sp > XB_SPIN_CAP) { atomicAdd(&(bar)[XB_TMO], 1u); break; } } } } while (0)
; __device__ __forceinline__ void xcd_barrier(const XcdBarrier& b) {
;     ...
;         const unsigned old = xb_add(&bar[XB_XSUB(b.x)], 1u);
;         const unsigned gen = old / nloc;
;         if (old + 1u == (gen + 1u) * nloc) {
;             __builtin_amdgcn_fence(__ATOMIC_RELEASE, "agent");
;             asm volatile("s_waitcnt vmcnt(0)" ::: "memory");
;             const unsigned og = xb_add(&bar[XB_TOP], 1u);
;             const unsigned tg = og / nx;
;             if (og + 1u == (tg + 1u) * nx) xb_add(&bar[XB_TOPGEN], 1u);
;             else XB_SPIN(xb_ld(&bar[XB_TOPGEN]) == tg, bar);
;             __builtin_amdgcn_fence(__ATOMIC_ACQUIRE, "agent");
;             xb_add(&bar[XB_XGEN(b.x)], 1u);
;             asm volatile("s_waitcnt vmcnt(0)" ::: "memory");
;         } else {
;             XB_SPIN(xb_ld(&bar[XB_XGEN(b.x)]) == gen, bar);
.Lxs_nofirst_8:
	v_mov_b32_e32 v0, 0x33500
	global_load_dword v0, v0, s[18:19] sc1
	s_add_u32 s28, s18, 0x33500
	s_addc_u32 s29, s19, 0
	s_waitcnt vmcnt(0)
	v_cmp_eq_u32_e32 vcc, v0, v1
	s_and_saveexec_b64 s[24:25], vcc
	s_cbranch_execz .LBB0_791
	s_add_u32 s26, s18, 0x30200
	s_addc_u32 s27, s19, 0
	s_mov_b32 s3, 1
	s_mov_b64 s[30:31], 0
	v_mov_b32_e32 v0, 0
	s_branch .LBB0_782

; __device__ __forceinline__ unsigned xb_ld(unsigned* p)              { return __hip_atomic_load(p, __ATOMIC_RELAXED, __HIP_MEMORY_SCOPE_AGENT); }
; __device__ __forceinline__ unsigned xb_add(unsigned* p, unsigned v) { return __hip_atomic_fetch_add(p, v, __ATOMIC_RELAXED, __HIP_MEMORY_SCOPE_AGENT); }
; #define XB_SPIN(cond, bar) do { unsigned _sp = 0; while (cond) { __builtin_amdgcn_s_sleep(1); \
;     if ((++_sp & 255u) == 0u) { if (xb_ld(&(bar)[XB_TMO])) break; if (_sp > XB_SPIN_CAP) { atomicAdd(&(bar)[XB_TMO], 1u); break; } } } } while (0)
; __device__ __forceinline__ void xcd_barrier(const XcdBarrier& b) {
;     ...
;             const unsigned og = xb_add(&bar[XB_TOP], 1u);
;             const unsigned tg = og / nx;
;             if (og + 1u == (tg + 1u) * nx) xb_add(&bar[XB_TOPGEN], 1u);
;             else XB_SPIN(xb_ld(&bar[XB_TOPGEN]) == tg, bar);
;             __builtin_amdgcn_fence(__ATOMIC_ACQUIRE, "agent");
;             xb_add(&bar[XB_XGEN(b.x)], 1u);
;             asm volatile("s_waitcnt vmcnt(0)" ::: "memory");
.LBB0_809:
	s_or_b64 exec, exec, s[14:15]
	s_mov_b64 s[14:15], exec
	v_mbcnt_lo_u32_b32 v0, s14, 0
	v_mbcnt_hi_u32_b32 v0, s15, v0
	v_cmp_eq_u32_e32 vcc, 0, v0
	s_waitcnt vmcnt(0)
	s_and_saveexec_b64 s[24:25], vcc
	s_cbranch_execz .LBB0_811
	s_bcnt1_i32_b64 s3, s[14:15]
.LBB0_811:
	s_or_b64 exec, exec, s[24:25]
	s_waitcnt vmcnt(0)

; __device__ __forceinline__ unsigned xb_ld(unsigned* p)              { return __hip_atomic_load(p, __ATOMIC_RELAXED, __HIP_MEMORY_SCOPE_AGENT); }
; __device__ __forceinline__ unsigned xb_add(unsigned* p, unsigned v) { return __hip_atomic_fetch_add(p, v, __ATOMIC_RELAXED, __HIP_MEMORY_SCOPE_AGENT); }
; #define XB_SPIN(cond, bar) do { unsigned _sp = 0; while (cond) { __builtin_amdgcn_s_sleep(1); \
;     if ((++_sp & 255u) == 0u) { if (xb_ld(&(bar)[XB_TMO])) break; if (_sp > XB_SPIN_CAP) { atomicAdd(&(bar)[XB_TMO], 1u); break; } } } } while (0)
; __device__ __forceinline__ void xcd_barrier(const XcdBarrier& b) {
;     ...
;             const unsigned og = xb_add(&bar[XB_TOP], 1u);
;             const unsigned tg = og / nx;
;             if (og + 1u == (tg + 1u) * nx) xb_add(&bar[XB_TOPGEN], 1u);
;             else XB_SPIN(xb_ld(&bar[XB_TOPGEN]) == tg, bar);
;             __builtin_amdgcn_fence(__ATOMIC_ACQUIRE, "agent");
;             xb_add(&bar[XB_XGEN(b.x)], 1u);
;             asm volatile("s_waitcnt vmcnt(0)" ::: "memory");
.LBB0_881:
	s_or_b64 exec, exec, s[14:15]
	s_mov_b64 s[14:15], exec
	v_mbcnt_lo_u32_b32 v0, s14, 0
	v_mbcnt_hi_u32_b32 v0, s15, v0
	v_cmp_eq_u32_e32 vcc, 0, v0
	s_waitcnt vmcnt(0)
	s_and_saveexec_b64 s[24:25], vcc
	s_cbranch_execz .LBB0_883
	s_bcnt1_i32_b64 s3, s[14:15]
.LBB0_883:
	s_or_b64 exec, exec, s[24:25]
	s_waitcnt vmcnt(0)

; __device__ __forceinline__ unsigned xb_ld(unsigned* p)              { return __hip_atomic_load(p, __ATOMIC_RELAXED, __HIP_MEMORY_SCOPE_AGENT); }
; __device__ __forceinline__ unsigned xb_add(unsigned* p, unsigned v) { return __hip_atomic_fetch_add(p, v, __ATOMIC_RELAXED, __HIP_MEMORY_SCOPE_AGENT); }
; #define XB_SPIN(cond, bar) do { unsigned _sp = 0; while (cond) { __builtin_amdgcn_s_sleep(1); \
;     if ((++_sp & 255u) == 0u) { if (xb_ld(&(bar)[XB_TMO])) break; if (_sp > XB_SPIN_CAP) { atomicAdd(&(bar)[XB_TMO], 1u); break; } } } } while (0)
; __device__ __forceinline__ void xcd_barrier(const XcdBarrier& b) {
;     ...
;         const unsigned old = xb_add(&bar[XB_XSUB(b.x)], 1u);
;         const unsigned gen = old / nloc;
;         if (old + 1u == (gen + 1u) * nloc) {
;             __builtin_amdgcn_fence(__ATOMIC_RELEASE, "agent");
;             asm volatile("s_waitcnt vmcnt(0)" ::: "memory");
;             const unsigned og = xb_add(&bar[XB_TOP], 1u);
;             const unsigned tg = og / nx;
;             if (og + 1u == (tg + 1u) * nx) xb_add(&bar[XB_TOPGEN], 1u);
;             else XB_SPIN(xb_ld(&bar[XB_TOPGEN]) == tg, bar);
;             __builtin_amdgcn_fence(__ATOMIC_ACQUIRE, "agent");
;             xb_add(&bar[XB_XGEN(b.x)], 1u);
;             asm volatile("s_waitcnt vmcnt(0)" ::: "memory");
;         } else {
;             XB_SPIN(xb_ld(&bar[XB_XGEN(b.x)]) == gen, bar);
.Lxs_nofirst_10:
	v_mov_b32_e32 v0, 0x33500
	global_load_dword v0, v0, s[18:19] sc1
	s_add_u32 s26, s18, 0x33500
	s_addc_u32 s27, s19, 0
	s_waitcnt vmcnt(0)
	v_cmp_eq_u32_e32 vcc, v0, v1
	s_and_saveexec_b64 s[22:23], vcc
	s_cbranch_execz .LBB0_917
	s_add_u32 s24, s18, 0x30200
	s_addc_u32 s25, s19, 0
	s_mov_b32 s3, 1
	s_mov_b64 s[28:29], 0
	v_mov_b32_e32 v0, 0
	s_branch .LBB0_908

; __device__ __forceinline__ unsigned xb_ld(unsigned* p)              { return __hip_atomic_load(p, __ATOMIC_RELAXED, __HIP_MEMORY_SCOPE_AGENT); }
; __device__ __forceinline__ unsigned xb_add(unsigned* p, unsigned v) { return __hip_atomic_fetch_add(p, v, __ATOMIC_RELAXED, __HIP_MEMORY_SCOPE_AGENT); }
; #define XB_SPIN(cond, bar) do { unsigned _sp = 0; while (cond) { __builtin_amdgcn_s_sleep(1); \
;     if ((++_sp & 255u) == 0u) { if (xb_ld(&(bar)[XB_TMO])) break; if (_sp > XB_SPIN_CAP) { atomicAdd(&(bar)[XB_TMO], 1u); break; } } } } while (0)
; __device__ __forceinline__ void xcd_barrier(const XcdBarrier& b) {
;     ...
;             const unsigned og = xb_add(&bar[XB_TOP], 1u);
;             const unsigned tg = og / nx;
;             if (og + 1u == (tg + 1u) * nx) xb_add(&bar[XB_TOPGEN], 1u);
;             else XB_SPIN(xb_ld(&bar[XB_TOPGEN]) == tg, bar);
;             __builtin_amdgcn_fence(__ATOMIC_ACQUIRE, "agent");
;             xb_add(&bar[XB_XGEN(b.x)], 1u);
;             asm volatile("s_waitcnt vmcnt(0)" ::: "memory");
.LBB0_935:
	s_or_b64 exec, exec, s[14:15]
	s_mov_b64 s[14:15], exec
	v_mbcnt_lo_u32_b32 v0, s14, 0
	v_mbcnt_hi_u32_b32 v0, s15, v0
	v_cmp_eq_u32_e32 vcc, 0, v0
	s_waitcnt vmcnt(0)
	s_and_saveexec_b64 s[22:23], vcc
	s_cbranch_execz .LBB0_937
	s_bcnt1_i32_b64 s3, s[14:15]
.LBB0_937:
	s_or_b64 exec, exec, s[22:23]
	s_waitcnt vmcnt(0)

; __device__ __forceinline__ unsigned xb_ld(unsigned* p)              { return __hip_atomic_load(p, __ATOMIC_RELAXED, __HIP_MEMORY_SCOPE_AGENT); }
; __device__ __forceinline__ unsigned xb_add(unsigned* p, unsigned v) { return __hip_atomic_fetch_add(p, v, __ATOMIC_RELAXED, __HIP_MEMORY_SCOPE_AGENT); }
; #define XB_SPIN(cond, bar) do { unsigned _sp = 0; while (cond) { __builtin_amdgcn_s_sleep(1); \
;     if ((++_sp & 255u) == 0u) { if (xb_ld(&(bar)[XB_TMO])) break; if (_sp > XB_SPIN_CAP) { atomicAdd(&(bar)[XB_TMO], 1u); break; } } } } while (0)
; __device__ __forceinline__ void xcd_barrier(const XcdBarrier& b) {
;     ...
;         const unsigned old = xb_add(&bar[XB_XSUB(b.x)], 1u);
;         const unsigned gen = old / nloc;
;         if (old + 1u == (gen + 1u) * nloc) {
;             __builtin_amdgcn_fence(__ATOMIC_RELEASE, "agent");
;             asm volatile("s_waitcnt vmcnt(0)" ::: "memory");
;             const unsigned og = xb_add(&bar[XB_TOP], 1u);
;             const unsigned tg = og / nx;
;             if (og + 1u == (tg + 1u) * nx) xb_add(&bar[XB_TOPGEN], 1u);
;             else XB_SPIN(xb_ld(&bar[XB_TOPGEN]) == tg, bar);
;             __builtin_amdgcn_fence(__ATOMIC_ACQUIRE, "agent");
;             xb_add(&bar[XB_XGEN(b.x)], 1u);
;             asm volatile("s_waitcnt vmcnt(0)" ::: "memory");
;         } else {
;             XB_SPIN(xb_ld(&bar[XB_XGEN(b.x)]) == gen, bar);
.Lxs_nofirst_11:
	v_mov_b32_e32 v0, 0x33500
	global_load_dword v0, v0, s[18:19] sc1
	s_add_u32 s20, s18, 0x33500
	s_addc_u32 s21, s19, 0
	s_waitcnt vmcnt(0)
	v_cmp_eq_u32_e32 vcc, v0, v1
	s_and_saveexec_b64 s[12:13], vcc
	s_cbranch_execz .LBB0_981
	s_add_u32 s14, s18, 0x30200
	s_addc_u32 s15, s19, 0
	s_mov_b32 s3, 1
	s_mov_b64 s[22:23], 0
	v_mov_b32_e32 v0, 0
	s_branch .LBB0_972

; __device__ __forceinline__ unsigned xb_ld(unsigned* p)              { return __hip_atomic_load(p, __ATOMIC_RELAXED, __HIP_MEMORY_SCOPE_AGENT); }
; __device__ __forceinline__ unsigned xb_add(unsigned* p, unsigned v) { return __hip_atomic_fetch_add(p, v, __ATOMIC_RELAXED, __HIP_MEMORY_SCOPE_AGENT); }
; #define XB_SPIN(cond, bar) do { unsigned _sp = 0; while (cond) { __builtin_amdgcn_s_sleep(1); \
;     if ((++_sp & 255u) == 0u) { if (xb_ld(&(bar)[XB_TMO])) break; if (_sp > XB_SPIN_CAP) { atomicAdd(&(bar)[XB_TMO], 1u); break; } } } } while (0)
; __device__ __forceinline__ void xcd_barrier(const XcdBarrier& b) {
;     ...
;             const unsigned og = xb_add(&bar[XB_TOP], 1u);
;             const unsigned tg = og / nx;
;             if (og + 1u == (tg + 1u) * nx) xb_add(&bar[XB_TOPGEN], 1u);
;             else XB_SPIN(xb_ld(&bar[XB_TOPGEN]) == tg, bar);
;             __builtin_amdgcn_fence(__ATOMIC_ACQUIRE, "agent");
;             xb_add(&bar[XB_XGEN(b.x)], 1u);
;             asm volatile("s_waitcnt vmcnt(0)" ::: "memory");
.LBB0_999:
	s_or_b64 exec, exec, s[10:11]
	s_mov_b64 s[10:11], exec
	v_mbcnt_lo_u32_b32 v0, s10, 0
	v_mbcnt_hi_u32_b32 v0, s11, v0
	v_cmp_eq_u32_e32 vcc, 0, v0
	s_waitcnt vmcnt(0)
	s_and_saveexec_b64 s[12:13], vcc
	s_cbranch_execz .LBB0_1001
	s_bcnt1_i32_b64 s3, s[10:11]
.LBB0_1001:
	s_or_b64 exec, exec, s[12:13]
	s_waitcnt vmcnt(0)
